# weight conversion prologue stores the bf16 weights with nt (written once, read in later phases)
# speedup vs baseline: 1.0142x; 1.0002x over previous
; #define LAS __attribute__((address_space(3)))
; #define LDS_WAIT() asm volatile("s_waitcnt lgkmcnt(0)" ::: "memory")
; template <bool MAPW = false>
; __device__ __forceinline__ void transpose_item(const float* W, int K, int N, bf16* WT, int k0, int n0, int drow0, LAS float* scr, int lane) {
; #pragma unroll 8
;     for (int i = 0; i < 32; ++i) { const int kk = 2 * i + (lane >> 5); scr[kk * 33 + (lane & 31)] = W[(size_t)(k0 + kk) * N + n0 + (lane & 31)]; }
;     LDS_WAIT(); asm volatile("" ::: "memory");
.LBB0_13:
	s_lshl_b32 s35, s15, 1
	s_lshl_b32 s36, s30, 1
	v_or_b32_e32 v11, s36, v2
	s_add_i32 s37, s35, 4
	s_add_i32 s38, s36, 4
	s_add_i32 s44, s36, 8
	v_add_u32_e32 v4, s12, v11
	v_or_b32_e32 v19, s37, v1
	v_or_b32_e32 v42, s38, v2
	v_mov_b32_e32 v23, v5
	v_or_b32_e32 v9, s35, v1
	s_add_i32 s46, s36, 12
	v_or_b32_e32 v44, s44, v2
	v_lshlrev_b64 v[36:37], 13, v[4:5]
	v_add_u32_e32 v22, s13, v19
	v_add_u32_e32 v4, s12, v42
	v_mov_b32_e32 v21, v5
	s_add_i32 s39, s35, 8
	s_add_i32 s45, s35, 12
	s_add_i32 s48, s36, 16
	v_add_u32_e32 v20, s13, v9
	v_or_b32_e32 v46, s46, v2
	v_lshlrev_b64 v[22:23], 13, v[22:23]
	v_lshlrev_b64 v[38:39], 13, v[4:5]
	v_add_u32_e32 v4, s12, v44
	s_add_i32 s50, s36, 20
	v_or_b32_e32 v43, s39, v1
	v_or_b32_e32 v45, s45, v1
	v_or_b32_e32 v48, s48, v2
	v_lshlrev_b64 v[20:21], 13, v[20:21]
	v_lshl_add_u64 v[36:37], v[12:13], 0, v[36:37]
	v_lshl_add_u64 v[22:23], v[12:13], 0, v[22:23]
	v_lshlrev_b64 v[40:41], 13, v[4:5]
	v_add_u32_e32 v4, s12, v46
	v_mov_b32_e32 v25, v5
	v_mov_b32_e32 v27, v5
	s_add_i32 s47, s35, 16
	s_add_i32 s49, s35, 20
	s_add_i32 s52, s36, 24
	v_or_b32_e32 v50, s50, v2
	v_add_u32_e32 v24, s13, v43
	v_add_u32_e32 v26, s13, v45
	v_lshl_add_u64 v[20:21], v[12:13], 0, v[20:21]
	v_lshl_add_u64 v[38:39], v[12:13], 0, v[38:39]
	global_load_dword v55, v[36:37], off
	global_load_dword v56, v[20:21], off
	global_load_dword v57, v[38:39], off
	global_load_dword v58, v[22:23], off
	v_lshlrev_b64 v[22:23], 13, v[4:5]
	v_add_u32_e32 v4, s12, v48
	s_add_i32 s51, s35, 24
	s_add_i32 s35, s35, 28
	s_add_i32 s36, s36, 28
	v_or_b32_e32 v47, s47, v1
	v_or_b32_e32 v49, s49, v1
	v_or_b32_e32 v52, s52, v2
	v_lshlrev_b64 v[24:25], 13, v[24:25]
	v_lshlrev_b64 v[26:27], 13, v[26:27]
	v_lshl_add_u64 v[20:21], v[12:13], 0, v[40:41]
	v_lshl_add_u64 v[22:23], v[12:13], 0, v[22:23]
	v_lshlrev_b64 v[36:37], 13, v[4:5]
	v_add_u32_e32 v4, s12, v50
	v_mov_b32_e32 v29, v5
	v_mov_b32_e32 v31, v5
	v_or_b32_e32 v51, s51, v1
	v_or_b32_e32 v53, s35, v1
	v_or_b32_e32 v54, s36, v2
	v_add_u32_e32 v28, s13, v47
	v_add_u32_e32 v30, s13, v49
	v_lshl_add_u64 v[24:25], v[12:13], 0, v[24:25]
	v_lshl_add_u64 v[26:27], v[12:13], 0, v[26:27]
	global_load_dword v59, v[20:21], off
	global_load_dword v60, v[24:25], off
	global_load_dword v61, v[22:23], off
	global_load_dword v62, v[26:27], off
	v_lshlrev_b64 v[22:23], 13, v[4:5]
	v_add_u32_e32 v4, s12, v52
	v_mov_b32_e32 v33, v5
	v_mov_b32_e32 v35, v5
	v_add_u32_e32 v32, s13, v51
	v_add_u32_e32 v34, s13, v53
	v_lshlrev_b64 v[28:29], 13, v[28:29]
	v_lshlrev_b64 v[30:31], 13, v[30:31]
	v_lshl_add_u64 v[20:21], v[12:13], 0, v[36:37]
	v_lshl_add_u64 v[22:23], v[12:13], 0, v[22:23]
	v_lshlrev_b64 v[24:25], 13, v[4:5]
	v_add_u32_e32 v4, s12, v54
	v_lshlrev_b64 v[32:33], 13, v[32:33]
	v_lshlrev_b64 v[34:35], 13, v[34:35]
	v_lshl_add_u64 v[28:29], v[12:13], 0, v[28:29]
	v_lshl_add_u64 v[30:31], v[12:13], 0, v[30:31]
	global_load_dword v63, v[20:21], off
	global_load_dword v64, v[28:29], off
	global_load_dword v65, v[22:23], off
	global_load_dword v66, v[30:31], off
	v_lshl_add_u64 v[20:21], v[12:13], 0, v[24:25]
	v_lshlrev_b64 v[22:23], 13, v[4:5]
	v_lshl_add_u64 v[32:33], v[12:13], 0, v[32:33]
	v_lshl_add_u64 v[34:35], v[12:13], 0, v[34:35]
	v_lshl_add_u64 v[22:23], v[12:13], 0, v[22:23]
	global_load_dword v4, v[20:21], off
	global_load_dword v67, v[32:33], off
	global_load_dword v68, v[22:23], off
	global_load_dword v69, v[34:35], off
	s_add_i32 s30, s30, 16
	s_add_i32 s15, s15, 16
	s_add_i32 s31, s31, -16
	v_mad_u64_u32 v[20:21], s[36:37], v11, s23, v[6:7]
	s_cmp_lg_u32 s31, 0
	v_mad_u64_u32 v[22:23], s[36:37], v9, s23, v[6:7]
	v_mad_u64_u32 v[24:25], s[36:37], v42, s23, v[6:7]
	v_mad_u64_u32 v[26:27], s[36:37], v19, s23, v[6:7]
	v_mad_u64_u32 v[28:29], s[36:37], v44, s23, v[6:7]
	v_mad_u64_u32 v[30:31], s[36:37], v43, s23, v[6:7]
	v_mad_u64_u32 v[32:33], s[36:37], v46, s23, v[6:7]
	v_mad_u64_u32 v[34:35], s[36:37], v45, s23, v[6:7]
	v_mad_u64_u32 v[36:37], s[36:37], v48, s23, v[6:7]
	v_mad_u64_u32 v[38:39], s[36:37], v47, s23, v[6:7]
	v_mad_u64_u32 v[40:41], s[36:37], v50, s23, v[6:7]
	v_mad_u64_u32 v[42:43], s[36:37], v49, s23, v[6:7]
	v_mad_u64_u32 v[44:45], s[36:37], v52, s23, v[6:7]
	v_mad_u64_u32 v[46:47], s[36:37], v51, s23, v[6:7]
	v_mad_u64_u32 v[48:49], s[36:37], v54, s23, v[6:7]
	v_mad_u64_u32 v[50:51], s[36:37], v53, s23, v[6:7]
	s_waitcnt vmcnt(15)
	ds_write_b32 v20, v55
	s_waitcnt vmcnt(14)
	ds_write_b32 v22, v56
	s_waitcnt vmcnt(13)
	ds_write_b32 v24, v57
	s_waitcnt vmcnt(12)
	ds_write_b32 v26, v58
	s_waitcnt vmcnt(11)
	ds_write_b32 v28, v59
	s_waitcnt vmcnt(10)
	ds_write_b32 v30, v60
	s_waitcnt vmcnt(9)
	ds_write_b32 v32, v61
	s_waitcnt vmcnt(8)
	ds_write_b32 v34, v62
	s_waitcnt vmcnt(7)
	ds_write_b32 v36, v63
	s_waitcnt vmcnt(6)
	ds_write_b32 v38, v64
	s_waitcnt vmcnt(5)
	ds_write_b32 v40, v65
	s_waitcnt vmcnt(4)
	ds_write_b32 v42, v66
	s_waitcnt vmcnt(3)
	ds_write_b32 v44, v4
	s_waitcnt vmcnt(2)
	ds_write_b32 v46, v67
	s_waitcnt vmcnt(1)
	ds_write_b32 v48, v68
	s_waitcnt vmcnt(0)
	ds_write_b32 v50, v69
	s_cbranch_scc1 .LBB0_13
; #define LAS __attribute__((address_space(3)))
; #define LDS_WAIT() asm volatile("s_waitcnt lgkmcnt(0)" ::: "memory")
; __device__ __forceinline__ unsigned cvtpk(float lo, float hi) { const f32x2_t v = {lo, hi}; const bf16x2_t b = __builtin_convertvector(v, bf16x2_t); return __builtin_bit_cast(unsigned, b); }
; template <bool MAPW = false>
; __device__ __forceinline__ void transpose_item(const float* W, int K, int N, bf16* WT, int k0, int n0, int drow0, LAS float* scr, int lane) {
;     ...
;     const int c = lane & 7;
; #pragma unroll
;     for (int j = 0; j < 4; ++j) { const int n = (lane >> 3) + 8 * j; const LAS float* s = scr + (8 * c) * 33 + n;
;         v4u o; o.x = cvtpk(s[0 * 33], s[1 * 33]); o.y = cvtpk(s[2 * 33], s[3 * 33]); o.z = cvtpk(s[4 * 33], s[5 * 33]); o.w = cvtpk(s[6 * 33], s[7 * 33]);
;         *(v4u*)(WT + (size_t)(MAPW ? win_row(drow0 + n) : drow0 + n) * K + k0 + 8 * c) = o; }
;     LDS_WAIT(); asm volatile("" ::: "memory");
	s_waitcnt lgkmcnt(0)
	s_lshl_b64 s[30:31], s[10:11], 23
	s_add_u32 s10, s17, s30
	ds_read2_b32 v[12:13], v14 offset0:33 offset1:41
	ds_read2_b32 v[24:25], v14 offset1:8
	ds_read2_b32 v[26:27], v14 offset0:66 offset1:74
	ds_read2_b32 v[28:29], v14 offset0:99 offset1:107
	ds_read2_b32 v[30:31], v14 offset0:132 offset1:140
	ds_read2_b32 v[32:33], v14 offset0:165 offset1:173
	ds_read2_b32 v[34:35], v14 offset0:198 offset1:206
	ds_read2_b32 v[36:37], v14 offset0:231 offset1:239
	s_addc_u32 s13, s18, s31
	s_lshl_b32 s12, s12, 1
	s_add_u32 s12, s10, s12
	s_addc_u32 s13, s13, 0
	v_mov_b32_e32 v11, v5
	v_or_b32_e32 v4, s14, v7
	v_lshl_add_u64 v[38:39], s[12:13], 0, v[10:11]
	v_lshlrev_b32_e32 v4, 12, v4
	s_waitcnt lgkmcnt(6)
	v_cvt_pk_bf16_f32 v20, v24, v12
	s_waitcnt lgkmcnt(4)
	v_cvt_pk_bf16_f32 v21, v26, v28
	s_waitcnt lgkmcnt(2)
	v_cvt_pk_bf16_f32 v22, v30, v32
	s_waitcnt lgkmcnt(0)
	v_cvt_pk_bf16_f32 v23, v34, v36
	v_lshl_add_u64 v[40:41], v[38:39], 0, v[4:5]
	global_store_dwordx4 v[40:41], v[20:23], off nt
	v_or_b32_e32 v4, s14, v15
	v_lshlrev_b32_e32 v4, 12, v4
	v_cvt_pk_bf16_f32 v20, v25, v13
	v_cvt_pk_bf16_f32 v21, v27, v29
	v_cvt_pk_bf16_f32 v22, v31, v33
	v_cvt_pk_bf16_f32 v23, v35, v37
	ds_read2_b32 v[24:25], v14 offset0:49 offset1:57
	ds_read2_b32 v[26:27], v14 offset0:16 offset1:24
	ds_read2_b32 v[28:29], v14 offset0:82 offset1:90
	ds_read2_b32 v[30:31], v14 offset0:115 offset1:123
	ds_read2_b32 v[32:33], v14 offset0:148 offset1:156
	ds_read2_b32 v[34:35], v14 offset0:181 offset1:189
	ds_read2_b32 v[36:37], v14 offset0:214 offset1:222
	ds_read2_b32 v[40:41], v14 offset0:247 offset1:255
	v_lshl_add_u64 v[12:13], v[38:39], 0, v[4:5]
	v_or_b32_e32 v4, s14, v16
	v_lshlrev_b32_e32 v4, 12, v4
	global_store_dwordx4 v[12:13], v[20:23], off nt
	v_lshl_add_u64 v[12:13], v[38:39], 0, v[4:5]
	v_or_b32_e32 v4, s14, v17
	s_waitcnt lgkmcnt(6)
	v_cvt_pk_bf16_f32 v20, v26, v24
	s_waitcnt lgkmcnt(4)
	v_cvt_pk_bf16_f32 v21, v28, v30
	s_waitcnt lgkmcnt(2)
	v_cvt_pk_bf16_f32 v22, v32, v34
	s_waitcnt lgkmcnt(0)
	v_cvt_pk_bf16_f32 v23, v36, v40
	v_lshlrev_b32_e32 v4, 12, v4
	global_store_dwordx4 v[12:13], v[20:23], off nt
	v_lshl_add_u64 v[12:13], v[38:39], 0, v[4:5]
	s_mov_b64 s[12:13], 0
	v_cvt_pk_bf16_f32 v20, v27, v25
	v_cvt_pk_bf16_f32 v21, v29, v31
	v_cvt_pk_bf16_f32 v22, v33, v35
	v_cvt_pk_bf16_f32 v23, v37, v41
	global_store_dwordx4 v[12:13], v[20:23], off nt
	s_waitcnt lgkmcnt(0)

; #define LAS __attribute__((address_space(3)))
; #define LDS_WAIT() asm volatile("s_waitcnt lgkmcnt(0)" ::: "memory")
; template <bool MAPW = false>
; __device__ __forceinline__ void transpose_item(const float* W, int K, int N, bf16* WT, int k0, int n0, int drow0, LAS float* scr, int lane) {
; #pragma unroll 8
;     for (int i = 0; i < 32; ++i) { const int kk = 2 * i + (lane >> 5); scr[kk * 33 + (lane & 31)] = W[(size_t)(k0 + kk) * N + n0 + (lane & 31)]; }
;     LDS_WAIT(); asm volatile("" ::: "memory");
.LBB0_17:
	s_lshl_b32 s35, s15, 1
	s_lshl_b32 s36, s30, 1
	v_or_b32_e32 v11, s36, v2
	s_add_i32 s37, s35, 4
	s_add_i32 s38, s36, 4
	s_add_i32 s44, s36, 8
	v_add_u32_e32 v4, s12, v11
	v_or_b32_e32 v19, s37, v1
	v_or_b32_e32 v42, s38, v2
	v_mov_b32_e32 v23, v5
	v_or_b32_e32 v9, s35, v1
	s_add_i32 s46, s36, 12
	v_or_b32_e32 v44, s44, v2
	v_lshlrev_b64 v[36:37], 13, v[4:5]
	v_add_u32_e32 v22, s13, v19
	v_add_u32_e32 v4, s12, v42
	v_mov_b32_e32 v21, v5
	s_add_i32 s39, s35, 8
	s_add_i32 s45, s35, 12
	s_add_i32 s48, s36, 16
	v_add_u32_e32 v20, s13, v9
	v_or_b32_e32 v46, s46, v2
	v_lshlrev_b64 v[22:23], 13, v[22:23]
	v_lshlrev_b64 v[38:39], 13, v[4:5]
	v_add_u32_e32 v4, s12, v44
	s_add_i32 s50, s36, 20
	v_or_b32_e32 v43, s39, v1
	v_or_b32_e32 v45, s45, v1
	v_or_b32_e32 v48, s48, v2
	v_lshlrev_b64 v[20:21], 13, v[20:21]
	v_lshl_add_u64 v[36:37], v[12:13], 0, v[36:37]
	v_lshl_add_u64 v[22:23], v[12:13], 0, v[22:23]
	v_lshlrev_b64 v[40:41], 13, v[4:5]
	v_add_u32_e32 v4, s12, v46
	v_mov_b32_e32 v25, v5
	v_mov_b32_e32 v27, v5
	s_add_i32 s47, s35, 16
	s_add_i32 s49, s35, 20
	s_add_i32 s52, s36, 24
	v_or_b32_e32 v50, s50, v2
	v_add_u32_e32 v24, s13, v43
	v_add_u32_e32 v26, s13, v45
	v_lshl_add_u64 v[20:21], v[12:13], 0, v[20:21]
	v_lshl_add_u64 v[38:39], v[12:13], 0, v[38:39]
	global_load_dword v55, v[36:37], off
	global_load_dword v56, v[20:21], off
	global_load_dword v57, v[38:39], off
	global_load_dword v58, v[22:23], off
	v_lshlrev_b64 v[22:23], 13, v[4:5]
	v_add_u32_e32 v4, s12, v48
	s_add_i32 s51, s35, 24
	s_add_i32 s35, s35, 28
	s_add_i32 s36, s36, 28
	v_or_b32_e32 v47, s47, v1
	v_or_b32_e32 v49, s49, v1
	v_or_b32_e32 v52, s52, v2
	v_lshlrev_b64 v[24:25], 13, v[24:25]
	v_lshlrev_b64 v[26:27], 13, v[26:27]
	v_lshl_add_u64 v[20:21], v[12:13], 0, v[40:41]
	v_lshl_add_u64 v[22:23], v[12:13], 0, v[22:23]
	v_lshlrev_b64 v[36:37], 13, v[4:5]
	v_add_u32_e32 v4, s12, v50
	v_mov_b32_e32 v29, v5
	v_mov_b32_e32 v31, v5
	v_or_b32_e32 v51, s51, v1
	v_or_b32_e32 v53, s35, v1
	v_or_b32_e32 v54, s36, v2
	v_add_u32_e32 v28, s13, v47
	v_add_u32_e32 v30, s13, v49
	v_lshl_add_u64 v[24:25], v[12:13], 0, v[24:25]
	v_lshl_add_u64 v[26:27], v[12:13], 0, v[26:27]
	global_load_dword v59, v[20:21], off
	global_load_dword v60, v[24:25], off
	global_load_dword v61, v[22:23], off
	global_load_dword v62, v[26:27], off
	v_lshlrev_b64 v[22:23], 13, v[4:5]
	v_add_u32_e32 v4, s12, v52
	v_mov_b32_e32 v33, v5
	v_mov_b32_e32 v35, v5
	v_add_u32_e32 v32, s13, v51
	v_add_u32_e32 v34, s13, v53
	v_lshlrev_b64 v[28:29], 13, v[28:29]
	v_lshlrev_b64 v[30:31], 13, v[30:31]
	v_lshl_add_u64 v[20:21], v[12:13], 0, v[36:37]
	v_lshl_add_u64 v[22:23], v[12:13], 0, v[22:23]
	v_lshlrev_b64 v[24:25], 13, v[4:5]
	v_add_u32_e32 v4, s12, v54
	v_lshlrev_b64 v[32:33], 13, v[32:33]
	v_lshlrev_b64 v[34:35], 13, v[34:35]
	v_lshl_add_u64 v[28:29], v[12:13], 0, v[28:29]
	v_lshl_add_u64 v[30:31], v[12:13], 0, v[30:31]
	global_load_dword v63, v[20:21], off
	global_load_dword v64, v[28:29], off
	global_load_dword v65, v[22:23], off
	global_load_dword v66, v[30:31], off
	v_lshl_add_u64 v[20:21], v[12:13], 0, v[24:25]
	v_lshlrev_b64 v[22:23], 13, v[4:5]
	v_lshl_add_u64 v[32:33], v[12:13], 0, v[32:33]
	v_lshl_add_u64 v[34:35], v[12:13], 0, v[34:35]
	v_lshl_add_u64 v[22:23], v[12:13], 0, v[22:23]
	global_load_dword v4, v[20:21], off
	global_load_dword v67, v[32:33], off
	global_load_dword v68, v[22:23], off
	global_load_dword v69, v[34:35], off
	s_add_i32 s30, s30, 16
	s_add_i32 s15, s15, 16
	s_add_i32 s31, s31, -16
	v_mad_u64_u32 v[20:21], s[36:37], v11, s23, v[6:7]
	s_cmp_lg_u32 s31, 0
	v_mad_u64_u32 v[22:23], s[36:37], v9, s23, v[6:7]
	v_mad_u64_u32 v[24:25], s[36:37], v42, s23, v[6:7]
	v_mad_u64_u32 v[26:27], s[36:37], v19, s23, v[6:7]
	v_mad_u64_u32 v[28:29], s[36:37], v44, s23, v[6:7]
	v_mad_u64_u32 v[30:31], s[36:37], v43, s23, v[6:7]
	v_mad_u64_u32 v[32:33], s[36:37], v46, s23, v[6:7]
	v_mad_u64_u32 v[34:35], s[36:37], v45, s23, v[6:7]
	v_mad_u64_u32 v[36:37], s[36:37], v48, s23, v[6:7]
	v_mad_u64_u32 v[38:39], s[36:37], v47, s23, v[6:7]
	v_mad_u64_u32 v[40:41], s[36:37], v50, s23, v[6:7]
	v_mad_u64_u32 v[42:43], s[36:37], v49, s23, v[6:7]
	v_mad_u64_u32 v[44:45], s[36:37], v52, s23, v[6:7]
	v_mad_u64_u32 v[46:47], s[36:37], v51, s23, v[6:7]
	v_mad_u64_u32 v[48:49], s[36:37], v54, s23, v[6:7]
	v_mad_u64_u32 v[50:51], s[36:37], v53, s23, v[6:7]
	s_waitcnt vmcnt(15)
	ds_write_b32 v20, v55
	s_waitcnt vmcnt(14)
	ds_write_b32 v22, v56
	s_waitcnt vmcnt(13)
	ds_write_b32 v24, v57
	s_waitcnt vmcnt(12)
	ds_write_b32 v26, v58
	s_waitcnt vmcnt(11)
	ds_write_b32 v28, v59
	s_waitcnt vmcnt(10)
	ds_write_b32 v30, v60
	s_waitcnt vmcnt(9)
	ds_write_b32 v32, v61
	s_waitcnt vmcnt(8)
	ds_write_b32 v34, v62
	s_waitcnt vmcnt(7)
	ds_write_b32 v36, v63
	s_waitcnt vmcnt(6)
	ds_write_b32 v38, v64
	s_waitcnt vmcnt(5)
	ds_write_b32 v40, v65
	s_waitcnt vmcnt(4)
	ds_write_b32 v42, v66
	s_waitcnt vmcnt(3)
	ds_write_b32 v44, v4
	s_waitcnt vmcnt(2)
	ds_write_b32 v46, v67
	s_waitcnt vmcnt(1)
	ds_write_b32 v48, v68
	s_waitcnt vmcnt(0)
	ds_write_b32 v50, v69
	s_cbranch_scc1 .LBB0_17
; #define LAS __attribute__((address_space(3)))
; #define LDS_WAIT() asm volatile("s_waitcnt lgkmcnt(0)" ::: "memory")
; __device__ __forceinline__ unsigned cvtpk(float lo, float hi) { const f32x2_t v = {lo, hi}; const bf16x2_t b = __builtin_convertvector(v, bf16x2_t); return __builtin_bit_cast(unsigned, b); }
; template <bool MAPW = false>
; __device__ __forceinline__ void transpose_item(const float* W, int K, int N, bf16* WT, int k0, int n0, int drow0, LAS float* scr, int lane) {
;     ...
;     const int c = lane & 7;
; #pragma unroll
;     for (int j = 0; j < 4; ++j) { const int n = (lane >> 3) + 8 * j; const LAS float* s = scr + (8 * c) * 33 + n;
;         v4u o; o.x = cvtpk(s[0 * 33], s[1 * 33]); o.y = cvtpk(s[2 * 33], s[3 * 33]); o.z = cvtpk(s[4 * 33], s[5 * 33]); o.w = cvtpk(s[6 * 33], s[7 * 33]);
;         *(v4u*)(WT + (size_t)(MAPW ? win_row(drow0 + n) : drow0 + n) * K + k0 + 8 * c) = o; }
;     LDS_WAIT(); asm volatile("" ::: "memory");
	s_waitcnt lgkmcnt(0)
	s_lshl_b64 s[30:31], s[10:11], 22
	s_add_u32 s10, s19, s30
	ds_read2_b32 v[12:13], v14 offset0:33 offset1:41
	ds_read2_b32 v[24:25], v14 offset1:8
	ds_read2_b32 v[26:27], v14 offset0:66 offset1:74
	ds_read2_b32 v[28:29], v14 offset0:99 offset1:107
	ds_read2_b32 v[30:31], v14 offset0:132 offset1:140
	ds_read2_b32 v[32:33], v14 offset0:165 offset1:173
	ds_read2_b32 v[34:35], v14 offset0:198 offset1:206
	ds_read2_b32 v[36:37], v14 offset0:231 offset1:239
	s_addc_u32 s13, s20, s31
	s_lshl_b32 s12, s12, 1
	s_add_u32 s12, s10, s12
	s_addc_u32 s13, s13, 0
	v_mov_b32_e32 v11, v5
	v_or_b32_e32 v4, s14, v7
	v_lshl_add_u64 v[38:39], s[12:13], 0, v[10:11]
	v_lshlrev_b32_e32 v4, 11, v4
	s_waitcnt lgkmcnt(6)
	v_cvt_pk_bf16_f32 v20, v24, v12
	s_waitcnt lgkmcnt(4)
	v_cvt_pk_bf16_f32 v21, v26, v28
	s_waitcnt lgkmcnt(2)
	v_cvt_pk_bf16_f32 v22, v30, v32
	s_waitcnt lgkmcnt(0)
	v_cvt_pk_bf16_f32 v23, v34, v36
	v_lshl_add_u64 v[40:41], v[38:39], 0, v[4:5]
	global_store_dwordx4 v[40:41], v[20:23], off nt
	v_or_b32_e32 v4, s14, v15
	v_lshlrev_b32_e32 v4, 11, v4
	v_cvt_pk_bf16_f32 v20, v25, v13
	v_cvt_pk_bf16_f32 v21, v27, v29
	v_cvt_pk_bf16_f32 v22, v31, v33
	v_cvt_pk_bf16_f32 v23, v35, v37
	ds_read2_b32 v[24:25], v14 offset0:49 offset1:57
	ds_read2_b32 v[26:27], v14 offset0:16 offset1:24
	ds_read2_b32 v[28:29], v14 offset0:82 offset1:90
	ds_read2_b32 v[30:31], v14 offset0:115 offset1:123
	ds_read2_b32 v[32:33], v14 offset0:148 offset1:156
	ds_read2_b32 v[34:35], v14 offset0:181 offset1:189
	ds_read2_b32 v[36:37], v14 offset0:214 offset1:222
	ds_read2_b32 v[40:41], v14 offset0:247 offset1:255
	v_lshl_add_u64 v[12:13], v[38:39], 0, v[4:5]
	v_or_b32_e32 v4, s14, v16
	v_lshlrev_b32_e32 v4, 11, v4
	global_store_dwordx4 v[12:13], v[20:23], off nt
	v_lshl_add_u64 v[12:13], v[38:39], 0, v[4:5]
	v_or_b32_e32 v4, s14, v17
	s_waitcnt lgkmcnt(6)
	v_cvt_pk_bf16_f32 v20, v26, v24
	s_waitcnt lgkmcnt(4)
	v_cvt_pk_bf16_f32 v21, v28, v30
	s_waitcnt lgkmcnt(2)
	v_cvt_pk_bf16_f32 v22, v32, v34
	s_waitcnt lgkmcnt(0)
	v_cvt_pk_bf16_f32 v23, v36, v40
	v_lshlrev_b32_e32 v4, 11, v4
	global_store_dwordx4 v[12:13], v[20:23], off nt
	v_lshl_add_u64 v[12:13], v[38:39], 0, v[4:5]
	s_nop 0
	v_cvt_pk_bf16_f32 v20, v27, v25
	v_cvt_pk_bf16_f32 v21, v29, v31
	v_cvt_pk_bf16_f32 v22, v33, v35
	v_cvt_pk_bf16_f32 v23, v37, v41
	global_store_dwordx4 v[12:13], v[20:23], off nt
	s_waitcnt lgkmcnt(0)

; #define LAS __attribute__((address_space(3)))
; #define LDS_WAIT() asm volatile("s_waitcnt lgkmcnt(0)" ::: "memory")
; template <bool MAPW = false>
; __device__ __forceinline__ void transpose_item(const float* W, int K, int N, bf16* WT, int k0, int n0, int drow0, LAS float* scr, int lane) {
; #pragma unroll 8
;     for (int i = 0; i < 32; ++i) { const int kk = 2 * i + (lane >> 5); scr[kk * 33 + (lane & 31)] = W[(size_t)(k0 + kk) * N + n0 + (lane & 31)]; }
;     LDS_WAIT(); asm volatile("" ::: "memory");
.LBB0_21:
	s_lshl_b32 s36, s30, 1
	s_lshl_b32 s37, s31, 1
	v_or_b32_e32 v4, s36, v1
	v_or_b32_e32 v9, s37, v2
	s_add_i32 s38, s36, 4
	s_add_i32 s39, s37, 4
	s_add_i32 s44, s36, 8
	s_add_i32 s45, s37, 8
	s_add_i32 s46, s36, 12
	s_add_i32 s47, s37, 12
	s_add_i32 s48, s36, 16
	s_add_i32 s49, s37, 16
	s_add_i32 s50, s36, 20
	s_add_i32 s51, s37, 20
	s_add_i32 s52, s36, 24
	s_add_i32 s53, s37, 24
	s_add_i32 s36, s36, 28
	s_add_i32 s37, s37, 28
	v_add_u32_e32 v11, s15, v4
	v_add_u32_e32 v19, s12, v9
	v_or_b32_e32 v52, s38, v1
	v_or_b32_e32 v53, s39, v2
	v_or_b32_e32 v54, s44, v1
	v_or_b32_e32 v55, s45, v2
	v_or_b32_e32 v56, s46, v1
	v_or_b32_e32 v57, s47, v2
	v_or_b32_e32 v58, s48, v1
	v_or_b32_e32 v59, s49, v2
	v_or_b32_e32 v60, s50, v1
	v_or_b32_e32 v61, s51, v2
	v_or_b32_e32 v62, s52, v1
	v_or_b32_e32 v63, s53, v2
	v_or_b32_e32 v64, s36, v1
	v_or_b32_e32 v65, s37, v2
	v_mad_i64_i32 v[20:21], s[36:37], v19, s24, v[12:13]
	v_mad_i64_i32 v[22:23], s[36:37], v11, s24, v[12:13]
	v_add_u32_e32 v11, s15, v52
	v_add_u32_e32 v19, s12, v53
	v_add_u32_e32 v30, s15, v54
	v_add_u32_e32 v28, s12, v55
	v_add_u32_e32 v34, s15, v56
	v_add_u32_e32 v32, s12, v57
	v_add_u32_e32 v38, s15, v58
	v_add_u32_e32 v36, s12, v59
	v_add_u32_e32 v42, s15, v60
	v_add_u32_e32 v40, s12, v61
	v_add_u32_e32 v46, s15, v62
	v_add_u32_e32 v44, s12, v63
	v_add_u32_e32 v50, s15, v64
	v_add_u32_e32 v48, s12, v65
	v_mad_i64_i32 v[24:25], s[36:37], v19, s24, v[12:13]
	v_mad_i64_i32 v[26:27], s[36:37], v11, s24, v[12:13]
	v_mad_i64_i32 v[28:29], s[36:37], v28, s24, v[12:13]
	v_mad_i64_i32 v[30:31], s[36:37], v30, s24, v[12:13]
	v_mad_i64_i32 v[32:33], s[36:37], v32, s24, v[12:13]
	v_mad_i64_i32 v[34:35], s[36:37], v34, s24, v[12:13]
	v_mad_i64_i32 v[36:37], s[36:37], v36, s24, v[12:13]
	v_mad_i64_i32 v[38:39], s[36:37], v38, s24, v[12:13]
	v_mad_i64_i32 v[40:41], s[36:37], v40, s24, v[12:13]
	v_mad_i64_i32 v[42:43], s[36:37], v42, s24, v[12:13]
	v_mad_i64_i32 v[44:45], s[36:37], v44, s24, v[12:13]
	v_mad_i64_i32 v[46:47], s[36:37], v46, s24, v[12:13]
	v_mad_i64_i32 v[48:49], s[36:37], v48, s24, v[12:13]
	v_mad_i64_i32 v[50:51], s[36:37], v50, s24, v[12:13]
	global_load_dword v11, v[20:21], off
	global_load_dword v19, v[22:23], off
	global_load_dword v66, v[24:25], off
	global_load_dword v67, v[26:27], off
	global_load_dword v68, v[28:29], off
	global_load_dword v69, v[30:31], off
	global_load_dword v70, v[32:33], off
	global_load_dword v71, v[34:35], off
	global_load_dword v72, v[36:37], off
	global_load_dword v73, v[38:39], off
	global_load_dword v74, v[40:41], off
	global_load_dword v75, v[42:43], off
	global_load_dword v76, v[44:45], off
	global_load_dword v77, v[46:47], off
	global_load_dword v78, v[48:49], off
	global_load_dword v79, v[50:51], off
	s_add_i32 s31, s31, 16
	s_add_i32 s30, s30, 16
	s_add_i32 s35, s35, -16
	v_mad_u64_u32 v[20:21], s[36:37], v9, s23, v[6:7]
	s_cmp_lg_u32 s35, 0
	v_mad_u64_u32 v[22:23], s[36:37], v4, s23, v[6:7]
	v_mad_u64_u32 v[24:25], s[36:37], v53, s23, v[6:7]
	v_mad_u64_u32 v[26:27], s[36:37], v52, s23, v[6:7]
	v_mad_u64_u32 v[28:29], s[36:37], v55, s23, v[6:7]
	v_mad_u64_u32 v[30:31], s[36:37], v54, s23, v[6:7]
	v_mad_u64_u32 v[32:33], s[36:37], v57, s23, v[6:7]
	v_mad_u64_u32 v[34:35], s[36:37], v56, s23, v[6:7]
	v_mad_u64_u32 v[36:37], s[36:37], v59, s23, v[6:7]
	v_mad_u64_u32 v[38:39], s[36:37], v58, s23, v[6:7]
	v_mad_u64_u32 v[40:41], s[36:37], v61, s23, v[6:7]
	v_mad_u64_u32 v[42:43], s[36:37], v60, s23, v[6:7]
	v_mad_u64_u32 v[44:45], s[36:37], v63, s23, v[6:7]
	v_mad_u64_u32 v[46:47], s[36:37], v62, s23, v[6:7]
	v_mad_u64_u32 v[48:49], s[36:37], v65, s23, v[6:7]
	v_mad_u64_u32 v[50:51], s[36:37], v64, s23, v[6:7]
	s_waitcnt vmcnt(15)
	ds_write_b32 v20, v11
	s_waitcnt vmcnt(14)
	ds_write_b32 v22, v19
	s_waitcnt vmcnt(13)
	ds_write_b32 v24, v66
	s_waitcnt vmcnt(12)
	ds_write_b32 v26, v67
	s_waitcnt vmcnt(11)
	ds_write_b32 v28, v68
	s_waitcnt vmcnt(10)
	ds_write_b32 v30, v69
	s_waitcnt vmcnt(9)
	ds_write_b32 v32, v70
	s_waitcnt vmcnt(8)
	ds_write_b32 v34, v71
	s_waitcnt vmcnt(7)
	ds_write_b32 v36, v72
	s_waitcnt vmcnt(6)
	ds_write_b32 v38, v73
	s_waitcnt vmcnt(5)
	ds_write_b32 v40, v74
	s_waitcnt vmcnt(4)
	ds_write_b32 v42, v75
	s_waitcnt vmcnt(3)
	ds_write_b32 v44, v76
	s_waitcnt vmcnt(2)
	ds_write_b32 v46, v77
	s_waitcnt vmcnt(1)
	ds_write_b32 v48, v78
	s_waitcnt vmcnt(0)
	ds_write_b32 v50, v79
	s_cbranch_scc1 .LBB0_21
; #define LAS __attribute__((address_space(3)))
; #define LDS_WAIT() asm volatile("s_waitcnt lgkmcnt(0)" ::: "memory")
; __device__ __forceinline__ unsigned cvtpk(float lo, float hi) { const f32x2_t v = {lo, hi}; const bf16x2_t b = __builtin_convertvector(v, bf16x2_t); return __builtin_bit_cast(unsigned, b); }
; __device__ __forceinline__ int win_row(int dl) {
;     const int L = dl & 255;
;     const int p = (dl >= C_GATE && dl < C_GATE + 6144) ? (((L >> 3) & 1) * 128 + (L >> 6) * 32 + ((L >> 4) & 3) * 8 + (L & 7)) : (((L >> 5) & 1) * 128 + (L >> 6) * 32 + (L & 31));
;     return (dl & ~255) + p;
; }
; template <bool MAPW = false>
; __device__ __forceinline__ void transpose_item(const float* W, int K, int N, bf16* WT, int k0, int n0, int drow0, LAS float* scr, int lane) {
;     ...
;     const int c = lane & 7;
; #pragma unroll
;     for (int j = 0; j < 4; ++j) { const int n = (lane >> 3) + 8 * j; const LAS float* s = scr + (8 * c) * 33 + n;
;         v4u o; o.x = cvtpk(s[0 * 33], s[1 * 33]); o.y = cvtpk(s[2 * 33], s[3 * 33]); o.z = cvtpk(s[4 * 33], s[5 * 33]); o.w = cvtpk(s[6 * 33], s[7 * 33]);
;         *(v4u*)(WT + (size_t)(MAPW ? win_row(drow0 + n) : drow0 + n) * K + k0 + 8 * c) = o; }
;     LDS_WAIT(); asm volatile("" ::: "memory");
	s_sub_i32 s15, s14, 32
	s_cmpk_lg_i32 s13, 0x80
	s_cselect_b32 s15, s15, 0x4200
	s_mul_hi_i32 s30, s10, 0x4300000
	s_mul_i32 s10, s10, 0x4300000
	s_cmpk_lt_i32 s13, 0x80
	s_cselect_b32 s14, s14, s15
	s_add_u32 s10, s21, s10
	s_addc_u32 s15, s22, s30
	s_ashr_i32 s13, s12, 31
	s_lshl_b64 s[12:13], s[12:13], 1
	s_add_u32 s12, s10, s12
	s_addc_u32 s13, s15, s13
	s_add_i32 s10, s14, 0xffffd600
	s_waitcnt lgkmcnt(0)
	s_cmpk_lt_u32 s10, 0x1800
	v_mov_b32_e32 v11, v5
	v_or_b32_e32 v4, s14, v7
	s_cselect_b32 s10, 4, 2
	ds_read2_b32 v[12:13], v14 offset0:33 offset1:41
	ds_read2_b32 v[24:25], v14 offset1:8
	ds_read2_b32 v[26:27], v14 offset0:66 offset1:74
	ds_read2_b32 v[28:29], v14 offset0:99 offset1:107
	ds_read2_b32 v[30:31], v14 offset0:132 offset1:140
	ds_read2_b32 v[32:33], v14 offset0:165 offset1:173
	ds_read2_b32 v[34:35], v14 offset0:198 offset1:206
	ds_read2_b32 v[36:37], v14 offset0:231 offset1:239
	v_lshl_add_u64 v[38:39], s[12:13], 0, v[10:11]
	v_lshrrev_b32_e32 v9, 1, v4
	s_cselect_b32 s12, s25, 0x60
	v_lshlrev_b32_e32 v4, s10, v4
	v_and_b32_e32 v4, 0x80, v4
	v_and_b32_e32 v9, s12, v9
	v_bitop3_b32 v11, s14, v18, v7 bitop3:0xc8
	v_or3_b32 v40, v9, v11, v4
	v_or_b32_e32 v4, s14, v15
	v_ashrrev_i32_e32 v41, 31, v40
	v_lshrrev_b32_e32 v9, 1, v4
	v_lshlrev_b32_e32 v4, s10, v4
	s_cselect_b32 s13, 0xffffff07, s26
	v_mov_b32_e32 v11, s14
	s_waitcnt lgkmcnt(6)
	v_cvt_pk_bf16_f32 v20, v24, v12
	v_lshlrev_b64 v[40:41], 12, v[40:41]
	v_and_b32_e32 v4, 0x80, v4
	v_and_b32_e32 v9, s12, v9
	v_bitop3_b32 v12, s13, v11, v15 bitop3:0xe0
	s_waitcnt lgkmcnt(4)
	v_cvt_pk_bf16_f32 v21, v26, v28
	s_waitcnt lgkmcnt(2)
	v_cvt_pk_bf16_f32 v22, v30, v32
	s_waitcnt lgkmcnt(0)
	v_cvt_pk_bf16_f32 v23, v34, v36
	v_lshl_add_u64 v[40:41], v[38:39], 0, v[40:41]
	v_or3_b32 v12, v12, v9, v4
	global_store_dwordx4 v[40:41], v[20:23], off nt
	v_or_b32_e32 v4, s14, v16
	v_lshrrev_b32_e32 v9, 1, v4
	v_cvt_pk_bf16_f32 v20, v25, v13
	v_ashrrev_i32_e32 v13, 31, v12
	v_lshlrev_b64 v[12:13], 12, v[12:13]
	v_cvt_pk_bf16_f32 v21, v27, v29
	v_cvt_pk_bf16_f32 v22, v31, v33
	v_cvt_pk_bf16_f32 v23, v35, v37
	v_lshl_add_u64 v[12:13], v[38:39], 0, v[12:13]
	ds_read2_b32 v[24:25], v14 offset0:16 offset1:24
	ds_read2_b32 v[26:27], v14 offset0:49 offset1:57
	ds_read2_b32 v[28:29], v14 offset0:82 offset1:90
	ds_read2_b32 v[30:31], v14 offset0:115 offset1:123
	ds_read2_b32 v[32:33], v14 offset0:148 offset1:156
	ds_read2_b32 v[34:35], v14 offset0:181 offset1:189
	ds_read2_b32 v[36:37], v14 offset0:214 offset1:222
	ds_read2_b32 v[40:41], v14 offset0:247 offset1:255
	v_lshlrev_b32_e32 v4, s10, v4
	s_cselect_b32 s13, 0xffffff07, s27
	global_store_dwordx4 v[12:13], v[20:23], off nt
	v_and_b32_e32 v4, 0x80, v4
	v_and_b32_e32 v9, s12, v9
	v_bitop3_b32 v12, s13, v11, v16 bitop3:0xe0
	v_or3_b32 v12, v12, v9, v4
	v_ashrrev_i32_e32 v13, 31, v12
	v_or_b32_e32 v4, s14, v17
	v_lshlrev_b64 v[12:13], 12, v[12:13]
	v_lshrrev_b32_e32 v9, 1, v4
	v_lshlrev_b32_e32 v4, s10, v4
	s_cselect_b32 s10, 0xffffff07, s28
	s_waitcnt lgkmcnt(6)
	v_cvt_pk_bf16_f32 v20, v24, v26
	s_waitcnt lgkmcnt(4)
	v_cvt_pk_bf16_f32 v21, v28, v30
	s_waitcnt lgkmcnt(2)
	v_cvt_pk_bf16_f32 v22, v32, v34
	s_waitcnt lgkmcnt(0)
	v_cvt_pk_bf16_f32 v23, v36, v40
	v_lshl_add_u64 v[12:13], v[38:39], 0, v[12:13]
	v_and_b32_e32 v4, 0x80, v4
	v_and_b32_e32 v9, s12, v9
	v_bitop3_b32 v11, s10, v11, v17 bitop3:0xe0
	global_store_dwordx4 v[12:13], v[20:23], off nt
	v_or3_b32 v12, v11, v9, v4
	v_ashrrev_i32_e32 v13, 31, v12
	v_lshlrev_b64 v[12:13], 12, v[12:13]
	v_cvt_pk_bf16_f32 v20, v25, v27
	v_cvt_pk_bf16_f32 v21, v29, v31
	v_cvt_pk_bf16_f32 v22, v33, v35
	v_cvt_pk_bf16_f32 v23, v37, v41
	v_lshl_add_u64 v[12:13], v[38:39], 0, v[12:13]
	global_store_dwordx4 v[12:13], v[20:23], off nt
	s_waitcnt lgkmcnt(0)
	s_branch .LBB0_8
